# a6 + WPREP b1f fold: 32 serialized load pairs batched into two groups of 32 loads
# speedup vs baseline: 1.0156x; 1.0007x over previous
.LBB0_112:
	global_load_dword v16, v[6:7], off
	global_load_dword v32, v[4:5], off
	v_lshl_add_u64 v[4:5], v[4:5], 0, s[2:3]
	global_load_dword v17, v[6:7], off offset:256
	global_load_dword v33, v[4:5], off
	v_lshl_add_u64 v[4:5], v[4:5], 0, s[2:3]
	global_load_dword v18, v[6:7], off offset:512
	global_load_dword v34, v[4:5], off
	v_lshl_add_u64 v[4:5], v[4:5], 0, s[2:3]
	global_load_dword v19, v[6:7], off offset:768
	global_load_dword v35, v[4:5], off
	v_lshl_add_u64 v[4:5], v[4:5], 0, s[2:3]
	global_load_dword v20, v[6:7], off offset:1024
	global_load_dword v36, v[4:5], off
	v_lshl_add_u64 v[4:5], v[4:5], 0, s[2:3]
	global_load_dword v21, v[6:7], off offset:1280
	global_load_dword v37, v[4:5], off
	v_lshl_add_u64 v[4:5], v[4:5], 0, s[2:3]
	global_load_dword v22, v[6:7], off offset:1536
	global_load_dword v38, v[4:5], off
	v_lshl_add_u64 v[4:5], v[4:5], 0, s[2:3]
	global_load_dword v23, v[6:7], off offset:1792
	global_load_dword v39, v[4:5], off
	v_lshl_add_u64 v[4:5], v[4:5], 0, s[2:3]
	global_load_dword v24, v[6:7], off offset:2048
	global_load_dword v40, v[4:5], off
	v_lshl_add_u64 v[4:5], v[4:5], 0, s[2:3]
	global_load_dword v25, v[6:7], off offset:2304
	global_load_dword v41, v[4:5], off
	v_lshl_add_u64 v[4:5], v[4:5], 0, s[2:3]
	global_load_dword v26, v[6:7], off offset:2560
	global_load_dword v42, v[4:5], off
	v_lshl_add_u64 v[4:5], v[4:5], 0, s[2:3]
	global_load_dword v27, v[6:7], off offset:2816
	global_load_dword v43, v[4:5], off
	v_lshl_add_u64 v[4:5], v[4:5], 0, s[2:3]
	global_load_dword v28, v[6:7], off offset:3072
	global_load_dword v44, v[4:5], off
	v_lshl_add_u64 v[4:5], v[4:5], 0, s[2:3]
	global_load_dword v29, v[6:7], off offset:3328
	global_load_dword v45, v[4:5], off
	v_lshl_add_u64 v[4:5], v[4:5], 0, s[2:3]
	global_load_dword v30, v[6:7], off offset:3584
	global_load_dword v46, v[4:5], off
	v_lshl_add_u64 v[4:5], v[4:5], 0, s[2:3]
	global_load_dword v31, v[6:7], off offset:3840
	global_load_dword v47, v[4:5], off
	v_lshl_add_u64 v[4:5], v[4:5], 0, s[2:3]
	v_lshl_add_u64 v[6:7], s[4:5], 4, v[6:7]
	s_waitcnt vmcnt(0)
	v_fmac_f32_e32 v0, v16, v32
	v_fmac_f32_e32 v0, v17, v33
	v_fmac_f32_e32 v0, v18, v34
	v_fmac_f32_e32 v0, v19, v35
	v_fmac_f32_e32 v0, v20, v36
	v_fmac_f32_e32 v0, v21, v37
	v_fmac_f32_e32 v0, v22, v38
	v_fmac_f32_e32 v0, v23, v39
	v_fmac_f32_e32 v0, v24, v40
	v_fmac_f32_e32 v0, v25, v41
	v_fmac_f32_e32 v0, v26, v42
	v_fmac_f32_e32 v0, v27, v43
	v_fmac_f32_e32 v0, v28, v44
	v_fmac_f32_e32 v0, v29, v45
	v_fmac_f32_e32 v0, v30, v46
	v_fmac_f32_e32 v0, v31, v47
	global_load_dword v16, v[6:7], off
	global_load_dword v32, v[4:5], off
	v_lshl_add_u64 v[4:5], v[4:5], 0, s[2:3]
	global_load_dword v17, v[6:7], off offset:256
	global_load_dword v33, v[4:5], off
	v_lshl_add_u64 v[4:5], v[4:5], 0, s[2:3]
	global_load_dword v18, v[6:7], off offset:512
	global_load_dword v34, v[4:5], off
	v_lshl_add_u64 v[4:5], v[4:5], 0, s[2:3]
	global_load_dword v19, v[6:7], off offset:768
	global_load_dword v35, v[4:5], off
	v_lshl_add_u64 v[4:5], v[4:5], 0, s[2:3]
	global_load_dword v20, v[6:7], off offset:1024
	global_load_dword v36, v[4:5], off
	v_lshl_add_u64 v[4:5], v[4:5], 0, s[2:3]
	global_load_dword v21, v[6:7], off offset:1280
	global_load_dword v37, v[4:5], off
	v_lshl_add_u64 v[4:5], v[4:5], 0, s[2:3]
	global_load_dword v22, v[6:7], off offset:1536
	global_load_dword v38, v[4:5], off
	v_lshl_add_u64 v[4:5], v[4:5], 0, s[2:3]
	global_load_dword v23, v[6:7], off offset:1792
	global_load_dword v39, v[4:5], off
	v_lshl_add_u64 v[4:5], v[4:5], 0, s[2:3]
	global_load_dword v24, v[6:7], off offset:2048
	global_load_dword v40, v[4:5], off
	v_lshl_add_u64 v[4:5], v[4:5], 0, s[2:3]
	global_load_dword v25, v[6:7], off offset:2304
	global_load_dword v41, v[4:5], off
	v_lshl_add_u64 v[4:5], v[4:5], 0, s[2:3]
	global_load_dword v26, v[6:7], off offset:2560
	global_load_dword v42, v[4:5], off
	v_lshl_add_u64 v[4:5], v[4:5], 0, s[2:3]
	global_load_dword v27, v[6:7], off offset:2816
	global_load_dword v43, v[4:5], off
	v_lshl_add_u64 v[4:5], v[4:5], 0, s[2:3]
	global_load_dword v28, v[6:7], off offset:3072
	global_load_dword v44, v[4:5], off
	v_lshl_add_u64 v[4:5], v[4:5], 0, s[2:3]
	global_load_dword v29, v[6:7], off offset:3328
	global_load_dword v45, v[4:5], off
	v_lshl_add_u64 v[4:5], v[4:5], 0, s[2:3]
	global_load_dword v30, v[6:7], off offset:3584
	global_load_dword v46, v[4:5], off
	v_lshl_add_u64 v[4:5], v[4:5], 0, s[2:3]
	global_load_dword v31, v[6:7], off offset:3840
	global_load_dword v47, v[4:5], off
	v_lshl_add_u64 v[4:5], v[4:5], 0, s[2:3]
	v_lshl_add_u64 v[6:7], s[4:5], 4, v[6:7]
	s_waitcnt vmcnt(0)
	v_fmac_f32_e32 v0, v16, v32
	v_fmac_f32_e32 v0, v17, v33
	v_fmac_f32_e32 v0, v18, v34
	v_fmac_f32_e32 v0, v19, v35
	v_fmac_f32_e32 v0, v20, v36
	v_fmac_f32_e32 v0, v21, v37
	v_fmac_f32_e32 v0, v22, v38
	v_fmac_f32_e32 v0, v23, v39
	v_fmac_f32_e32 v0, v24, v40
	v_fmac_f32_e32 v0, v25, v41
	v_fmac_f32_e32 v0, v26, v42
	v_fmac_f32_e32 v0, v27, v43
	v_fmac_f32_e32 v0, v28, v44
	v_fmac_f32_e32 v0, v29, v45
	v_fmac_f32_e32 v0, v30, v46
	v_fmac_f32_e32 v0, v31, v47
	s_or_b64 exec, exec, s[8:9]
	ds_bpermute_b32 v4, v8, v0
	s_waitcnt lgkmcnt(0)
	v_add_f32_e32 v0, v0, v4
	ds_bpermute_b32 v4, v9, v0
	s_waitcnt lgkmcnt(0)
	v_add_f32_e32 v0, v0, v4
	ds_bpermute_b32 v4, v10, v0
	s_waitcnt lgkmcnt(0)
	v_add_f32_e32 v0, v0, v4
	ds_bpermute_b32 v4, v11, v0
	s_waitcnt lgkmcnt(0)
	v_add_f32_e32 v0, v0, v4
	ds_bpermute_b32 v4, v12, v0
	s_waitcnt lgkmcnt(0)
	v_add_f32_e32 v0, v0, v4
	ds_bpermute_b32 v4, v13, v0
	s_and_saveexec_b64 s[8:9], s[96:97]
	s_cbranch_execz .LBB0_110
	s_ashr_i32 s7, s6, 31
	s_lshl_b64 s[20:21], s[6:7], 2
	s_add_u32 s22, s18, s20
	s_addc_u32 s23, s19, s21
	s_add_u32 s20, s14, s20
	s_addc_u32 s21, s15, s21
	global_load_dword v5, v1, s[20:21]
	s_waitcnt lgkmcnt(0)
	v_add_f32_e32 v0, v0, v4
	s_waitcnt vmcnt(0)
	v_add_f32_e32 v0, v0, v5
	global_store_dword v1, v0, s[22:23]
	s_branch .LBB0_110
